# adds: D-combine loop no longer drains its own store before issuing the next iteration's loads
# speedup vs baseline: 1.0584x; 1.0584x over previous
; __device__ __forceinline__ unsigned pk2(float lo, float hi) { f32x2_t v = {lo, hi}; bf16x2_t b = __builtin_convertvector(v, bf16x2_t); return __builtin_bit_cast(unsigned, b); }
; __device__ __forceinline__ void dcombine_phase(float* dout, bf16* od) {
;     ...
;     for (int u = blockIdx.x * NTHREADS + tid; u < M * 32; u += gridDim.x * NTHREADS) {
;         const int tok = u >> 5, c0 = (u & 31) * 8;
;         v4u w = {0u, 0u, 0u, 0u};
;         if (c0 < 128) {
;             const int hs = c0 >> 6;
;             f32x4 a = {0.f, 0.f, 0.f, 0.f}, bq = a; float lsum = 0.f;
; #pragma unroll
;             for (int g = 0; g < 3; ++g) {
;                 const float* q = PO + ((size_t)g * M + tok) * 128 + c0;
;                 a = a + *(const f32x4*)q; bq = bq + *(const f32x4*)(q + 4);
;                 lsum += PL[((size_t)g * M + tok) * 2 + hs];
;             }
;             const float inv = 1.0f / lsum;
;             w.x = pk2(a[0] * inv, a[1] * inv); w.y = pk2(a[2] * inv, a[3] * inv); w.z = pk2(bq[0] * inv, bq[1] * inv); w.w = pk2(bq[2] * inv, bq[3] * inv);
;         }
;         *(v4u*)(od + (size_t)tok * 256 + c0) = w;
;     }
.LBB0_694:
	v_ashrrev_i32_e32 v8, 5, v10
	v_and_b32_e32 v12, 0xf8, v11
	s_movk_i32 s1, 0x7f
	v_cmp_lt_u32_e32 vcc, s1, v12
	v_ashrrev_i32_e32 v9, 31, v8
	s_and_saveexec_b64 s[2:3], vcc
	s_xor_b64 s[12:13], exec, s[2:3]
	v_lshlrev_b64 v[6:7], 9, v[8:9]
	s_or_saveexec_b64 s[12:13], s[12:13]
	v_mov_b32_e32 v2, 0
	v_mov_b32_e32 v3, 0
	v_mov_b32_e32 v4, 0
	v_mov_b32_e32 v5, 0
	s_xor_b64 exec, exec, s[12:13]
	s_cbranch_execz .LBB0_693
	v_lshlrev_b32_e32 v0, 2, v12
	v_lshl_add_u64 v[26:27], s[24:25], 0, v[0:1]
	v_lshrrev_b32_e32 v0, 4, v12
	s_mov_b64 s[2:3], 0x8000
	v_and_b32_e32 v0, 12, v0
	v_lshl_add_u64 v[22:23], v[8:9], 0, s[2:3]
	v_lshl_add_u64 v[34:35], s[8:9], 0, v[0:1]
	v_lshlrev_b64 v[6:7], 9, v[8:9]
	v_lshlrev_b64 v[20:21], 9, v[22:23]
	s_mov_b64 s[2:3], 0x10000
	v_lshl_add_u64 v[14:15], v[26:27], 0, v[6:7]
	v_lshl_add_u64 v[18:19], v[8:9], 3, v[34:35]
	v_lshl_add_u64 v[24:25], v[26:27], 0, v[20:21]
	v_lshl_add_u64 v[28:29], v[22:23], 3, v[34:35]
	v_lshl_add_u64 v[8:9], v[8:9], 0, s[2:3]
	global_load_dwordx4 v[2:5], v[14:15], off offset:16
	s_nop 0
	global_load_dwordx4 v[14:17], v[14:15], off
	s_nop 0
	global_load_dword v0, v[18:19], off
	s_nop 0
	global_load_dwordx4 v[18:21], v[24:25], off
	s_nop 0
	global_load_dwordx4 v[22:25], v[24:25], off offset:16
	s_nop 0
	global_load_dword v13, v[28:29], off
	v_lshlrev_b64 v[28:29], 9, v[8:9]
	v_lshl_add_u64 v[30:31], v[26:27], 0, v[28:29]
	v_lshl_add_u64 v[8:9], v[8:9], 3, v[34:35]
	global_load_dwordx4 v[26:29], v[30:31], off
	s_nop 0
	global_load_dwordx4 v[30:33], v[30:31], off offset:16
	s_waitcnt vmcnt(7)
	v_pk_add_f32 v[4:5], v[4:5], 0 op_sel_hi:[1,0]
	global_load_dword v34, v[8:9], off
	s_waitcnt vmcnt(6)
	v_add_f32_e32 v0, 0, v0
	s_waitcnt vmcnt(3)
	v_add_f32_e32 v0, v0, v13
	v_pk_add_f32 v[8:9], v[16:17], 0 op_sel_hi:[1,0]
	v_pk_add_f32 v[14:15], v[14:15], 0 op_sel_hi:[1,0]
	v_pk_add_f32 v[2:3], v[2:3], 0 op_sel_hi:[1,0]
	v_pk_add_f32 v[14:15], v[14:15], v[18:19]
	v_pk_add_f32 v[8:9], v[8:9], v[20:21]
	v_pk_add_f32 v[4:5], v[4:5], v[24:25]
	v_pk_add_f32 v[2:3], v[2:3], v[22:23]
	s_waitcnt vmcnt(2)
	v_pk_add_f32 v[8:9], v[8:9], v[28:29]
	v_pk_add_f32 v[14:15], v[14:15], v[26:27]
	s_waitcnt vmcnt(1)
	v_pk_add_f32 v[4:5], v[4:5], v[32:33]
	v_pk_add_f32 v[2:3], v[2:3], v[30:31]
	s_waitcnt vmcnt(0)
	v_add_f32_e32 v0, v0, v34
	v_div_scale_f32 v13, s[2:3], v0, v0, 1.0
	v_rcp_f32_e32 v16, v13
	v_div_scale_f32 v17, vcc, 1.0, v0, 1.0
	v_fma_f32 v18, -v13, v16, 1.0
	v_fmac_f32_e32 v16, v18, v16
	v_mul_f32_e32 v18, v17, v16
	v_fma_f32 v19, -v13, v18, v17
	v_fmac_f32_e32 v18, v19, v16
	v_fma_f32 v13, -v13, v18, v17
	v_div_fmas_f32 v13, v13, v16, v18
	v_div_fixup_f32 v0, v13, v0, 1.0
	v_pk_mul_f32 v[14:15], v[14:15], v[0:1] op_sel_hi:[1,0]
	v_pk_mul_f32 v[8:9], v[8:9], v[0:1] op_sel_hi:[1,0]
	v_pk_mul_f32 v[16:17], v[2:3], v[0:1] op_sel_hi:[1,0]
	v_pk_mul_f32 v[18:19], v[4:5], v[0:1] op_sel_hi:[1,0]
	v_cvt_pk_bf16_f32 v2, v14, v15
	v_cvt_pk_bf16_f32 v3, v8, v9
	v_cvt_pk_bf16_f32 v4, v16, v17
	v_cvt_pk_bf16_f32 v5, v18, v19
	s_branch .LBB0_693
